# combo6 + int8 up-projection units without an epilogue barrier keep the wave halves staggered across unit boundaries (align barrier only after the last unit, no re-stagger barrier)
# baseline (speedup 1.0000x reference)
; #define PG8_STAGE(bufoff, gbase, unused) do { _Pragma("unroll") for (int _i = 0; _i < 2; ++_i) \
;         __builtin_amdgcn_global_load_lds((const unsigned*)((const char*)(gbase) + voff + _i * 8192), (LAS unsigned*)(lds + (bufoff) + ldsw + _i * 8192), 16, 0, 0); } while (0)
; #define PG8_LDA(dst, b, h) do { _Pragma("unroll") for (int m = 0; m < 4; ++m) _Pragma("unroll") for (int k = 0; k < 2; ++k) dst[m][k] = *(const LAS bf16x8*)(lds + PG8_SA(b, h) + aoff + m * 2048 + (FP8 ? k * 16 : k * 1024)); } while (0)
; #define PG8_LDB(dst, b, h) do { _Pragma("unroll") for (int n = 0; n < 2; ++n) _Pragma("unroll") for (int k = 0; k < 2; ++k) dst[n][k] = *(const LAS bf16x8*)(lds + PG8_SB(b, h) + boff + n * 2048 + (FP8 ? k * 16 : k * 1024)); } while (0)
; #define PG8_WAIT_V(n) asm volatile("s_waitcnt vmcnt(" #n ")" ::: "memory")
; #define PG8_WAIT_L(n) asm volatile("s_waitcnt lgkmcnt(" #n ")" ::: "memory")
; #define PG8_BAR __builtin_amdgcn_s_barrier()
; #define PG8_SCHED __builtin_amdgcn_sched_barrier(0)
; template <class Epi, class Sched, bool ALIGN_EPI, bool SP2, int MODE  >
; __device__ __forceinline__ void gemm_phase(LAS unsigned char* lds, const Gemm g, const Sched S, const Epi E, unsigned long long& probe_acc, int epi_id, int wv) {
;     ...
;             PG8_LDB(B0, 0, 0); PG8_LDB(B1, 0, 1); PG8_SCHED; PG8_LDA(At, 0, 0); PG8_STAGE(PG8_SA(1, 1), a1 + hA, voffA);
;             PG8_WAIT_V(8); PG8_WAIT_L(0); PG8_BAR; PG8_MMA(0, 0, At, B0); PG8_MMA(0, 1, At, B1); PG8_BAR; PG8_SCHED;
;             PG8_LDA(At, 0, 1); PG8_STAGE(PG8_SB(0, 0), b2, voffB); PG8_STAGE(PG8_SB(0, 1), b2 + hB, voffB); PG8_STAGE(PG8_SA(0, 0), a2, voffA);
;             PG8_WAIT_V(8); PG8_WAIT_L(0); PG8_BAR; PG8_MMA(1, 0, At, B0); PG8_MMA(1, 1, At, B1); PG8_BAR; PG8_SCHED;
.LBB0_326:
	v_add_u32_e32 v0, s39, v212
	ds_read_b128 v[132:135], v0
	ds_read_b128 v[136:139], v0 offset:1024
	ds_read_b128 v[140:143], v0 offset:2048
	ds_read_b128 v[144:147], v0 offset:3072
	v_add_u32_e32 v0, s65, v212
	ds_read_b128 v[148:151], v0
	ds_read_b128 v[152:155], v0 offset:1024
	ds_read_b128 v[156:159], v0 offset:2048
	ds_read_b128 v[160:163], v0 offset:3072
	s_add_u32 s30, s28, 0x8000
	s_addc_u32 s31, s29, 0
	s_cmp_eq_u32 s14, 12
	s_cselect_b32 s23, s27, s31
	s_cselect_b32 s22, s46, s30
	s_cselect_b32 s21, vcc_lo, s17
	s_cselect_b32 s20, vcc_hi, s16
	v_lshl_add_u64 v[184:185], s[28:29], 0, v[130:131]
	v_lshl_add_u64 v[204:205], v[184:185], 0, s[80:81]
	s_add_i32 m0, s85, 0xc000
	ds_read_b128 v[164:167], v213
	ds_read_b128 v[168:171], v213 offset:1024
	ds_read_b128 v[172:175], v213 offset:2048
	ds_read_b128 v[176:179], v213 offset:3072
	ds_read_b128 v[180:183], v213 offset:4096
	ds_read_b128 v[190:193], v213 offset:5120
	ds_read_b128 v[196:199], v213 offset:6144
	ds_read_b128 v[200:203], v213 offset:7168
	global_load_lds_dwordx4 v[204:205], off
	v_lshl_add_u64 v[184:185], v[184:185], 0, s[82:83]
	s_add_i32 m0, s85, 0xe000
	s_nop 0
	global_load_lds_dwordx4 v[184:185], off
	s_waitcnt vmcnt(8)
	s_waitcnt lgkmcnt(0)
	s_setprio 1
	s_barrier
	v_mfma_i32_16x16x64_i8 v[126:129], v[132:135], v[164:167], v[126:129]
	v_mfma_i32_16x16x64_i8 v[102:105], v[140:143], v[164:167], v[102:105]
	v_mfma_i32_16x16x64_i8 v[122:125], v[132:135], v[172:175], v[122:125]
	v_mfma_i32_16x16x64_i8 v[94:97], v[140:143], v[172:175], v[94:97]
	v_mfma_i32_16x16x64_i8 v[118:121], v[132:135], v[180:183], v[118:121]
	v_mfma_i32_16x16x64_i8 v[46:49], v[140:143], v[180:183], v[46:49]
	v_mfma_i32_16x16x64_i8 v[110:113], v[132:135], v[196:199], v[110:113]
	v_mfma_i32_16x16x64_i8 v[38:41], v[140:143], v[196:199], v[38:41]
	v_mfma_i32_16x16x64_i8 v[126:129], v[136:139], v[168:171], v[126:129]
	v_mfma_i32_16x16x64_i8 v[102:105], v[144:147], v[168:171], v[102:105]
	v_mfma_i32_16x16x64_i8 v[122:125], v[136:139], v[176:179], v[122:125]
	v_mfma_i32_16x16x64_i8 v[94:97], v[144:147], v[176:179], v[94:97]
	v_mfma_i32_16x16x64_i8 v[118:121], v[136:139], v[190:193], v[118:121]
	v_mfma_i32_16x16x64_i8 v[46:49], v[144:147], v[190:193], v[46:49]
	v_mfma_i32_16x16x64_i8 v[110:113], v[136:139], v[200:203], v[110:113]
	v_mfma_i32_16x16x64_i8 v[38:41], v[144:147], v[200:203], v[38:41]
	v_mfma_i32_16x16x64_i8 v[114:117], v[148:151], v[164:167], v[114:117]
	v_mfma_i32_16x16x64_i8 v[82:85], v[156:159], v[164:167], v[82:85]
	v_mfma_i32_16x16x64_i8 v[106:109], v[148:151], v[172:175], v[106:109]
	v_mfma_i32_16x16x64_i8 v[74:77], v[156:159], v[172:175], v[74:77]
	v_mfma_i32_16x16x64_i8 v[98:101], v[148:151], v[180:183], v[98:101]
	v_mfma_i32_16x16x64_i8 v[42:45], v[156:159], v[180:183], v[42:45]
	v_mfma_i32_16x16x64_i8 v[90:93], v[148:151], v[196:199], v[90:93]
	v_mfma_i32_16x16x64_i8 v[34:37], v[156:159], v[196:199], v[34:37]
	v_mfma_i32_16x16x64_i8 v[114:117], v[152:155], v[168:171], v[114:117]
	v_mfma_i32_16x16x64_i8 v[82:85], v[160:163], v[168:171], v[82:85]
	v_mfma_i32_16x16x64_i8 v[106:109], v[152:155], v[176:179], v[106:109]
	v_mfma_i32_16x16x64_i8 v[74:77], v[160:163], v[176:179], v[74:77]
	v_mfma_i32_16x16x64_i8 v[98:101], v[152:155], v[190:193], v[98:101]
	v_mfma_i32_16x16x64_i8 v[42:45], v[160:163], v[190:193], v[42:45]
	v_mfma_i32_16x16x64_i8 v[90:93], v[152:155], v[200:203], v[90:93]
	v_mfma_i32_16x16x64_i8 v[34:37], v[160:163], v[200:203], v[34:37]
	s_barrier
	s_setprio 0
	s_mov_b32 m0, s41
	v_lshl_add_u64 v[184:185], s[20:21], 0, v[130:131]
	ds_read_b128 v[164:167], v213 offset:16384
	ds_read_b128 v[168:171], v213 offset:17408
	ds_read_b128 v[172:175], v213 offset:18432
	ds_read_b128 v[176:179], v213 offset:19456
	ds_read_b128 v[180:183], v213 offset:20480
	ds_read_b128 v[190:193], v213 offset:21504
	ds_read_b128 v[196:199], v213 offset:22528
	ds_read_b128 v[200:203], v213 offset:23552
	global_load_lds_dwordx4 v[184:185], off
	v_lshl_add_u64 v[204:205], v[184:185], 0, s[70:71]
	s_mov_b32 m0, s64
	s_nop 0
	global_load_lds_dwordx4 v[204:205], off
	v_lshl_add_u64 v[204:205], v[184:185], 0, s[72:73]
	s_mov_b32 m0, s68
	s_nop 0
	global_load_lds_dwordx4 v[204:205], off
	v_lshl_add_u64 v[204:205], v[184:185], 0, s[74:75]
	s_mov_b32 m0, s84
	s_nop 0
	global_load_lds_dwordx4 v[204:205], off
	v_lshl_add_u64 v[204:205], s[22:23], 0, v[130:131]
	s_mov_b32 m0, s85
	v_lshl_add_u64 v[206:207], v[204:205], 0, s[70:71]
	global_load_lds_dwordx4 v[204:205], off
	s_mov_b32 m0, s86
	s_nop 0
	global_load_lds_dwordx4 v[206:207], off
	s_waitcnt vmcnt(8)
	s_waitcnt lgkmcnt(0)
	s_setprio 1
	s_barrier
; #define PG8_STAGE(bufoff, gbase, unused) do { _Pragma("unroll") for (int _i = 0; _i < 2; ++_i) \
;         __builtin_amdgcn_global_load_lds((const unsigned*)((const char*)(gbase) + voff + _i * 8192), (LAS unsigned*)(lds + (bufoff) + ldsw + _i * 8192), 16, 0, 0); } while (0)
; #define PG8_LDA(dst, b, h) do { _Pragma("unroll") for (int m = 0; m < 4; ++m) _Pragma("unroll") for (int k = 0; k < 2; ++k) dst[m][k] = *(const LAS bf16x8*)(lds + PG8_SA(b, h) + aoff + m * 2048 + (FP8 ? k * 16 : k * 1024)); } while (0)
; #define PG8_LDB(dst, b, h) do { _Pragma("unroll") for (int n = 0; n < 2; ++n) _Pragma("unroll") for (int k = 0; k < 2; ++k) dst[n][k] = *(const LAS bf16x8*)(lds + PG8_SB(b, h) + boff + n * 2048 + (FP8 ? k * 16 : k * 1024)); } while (0)
; #define PG8_WAIT_V(n) asm volatile("s_waitcnt vmcnt(" #n ")" ::: "memory")
; #define PG8_WAIT_L(n) asm volatile("s_waitcnt lgkmcnt(" #n ")" ::: "memory")
; #define PG8_BAR __builtin_amdgcn_s_barrier()
; #define PG8_SCHED __builtin_amdgcn_sched_barrier(0)
; template <class Epi, class Sched, bool ALIGN_EPI, bool SP2, int MODE  >
; __device__ __forceinline__ void gemm_phase(LAS unsigned char* lds, const Gemm g, const Sched S, const Epi E, unsigned long long& probe_acc, int epi_id, int wv) {
;     ...
;             PG8_LDA(At, 0, 1); PG8_STAGE(PG8_SB(0, 0), b2, voffB); PG8_STAGE(PG8_SB(0, 1), b2 + hB, voffB); PG8_STAGE(PG8_SA(0, 0), a2, voffA);
;             PG8_WAIT_V(8); PG8_WAIT_L(0); PG8_BAR; PG8_MMA(1, 0, At, B0); PG8_MMA(1, 1, At, B1); PG8_BAR; PG8_SCHED;
;             PG8_LDB(B0, 1, 0); PG8_LDB(B1, 1, 1); PG8_SCHED; PG8_LDA(At, 1, 0); PG8_STAGE(PG8_SA(0, 1), a2 + hA, voffA);
;             PG8_WAIT_V(8); PG8_WAIT_L(0); PG8_BAR; PG8_MMA(0, 0, At, B0); PG8_MMA(0, 1, At, B1); PG8_BAR; PG8_SCHED;
	v_mfma_i32_16x16x64_i8 v[86:89], v[132:135], v[164:167], v[86:89]
	v_mfma_i32_16x16x64_i8 v[30:33], v[140:143], v[164:167], v[30:33]
	v_mfma_i32_16x16x64_i8 v[78:81], v[132:135], v[172:175], v[78:81]
	v_mfma_i32_16x16x64_i8 v[22:25], v[140:143], v[172:175], v[22:25]
	v_mfma_i32_16x16x64_i8 v[70:73], v[132:135], v[180:183], v[70:73]
	v_mfma_i32_16x16x64_i8 v[14:17], v[140:143], v[180:183], v[14:17]
	v_mfma_i32_16x16x64_i8 v[62:65], v[132:135], v[196:199], v[62:65]
	v_mfma_i32_16x16x64_i8 v[2:5], v[140:143], v[196:199], v[2:5]
	v_mfma_i32_16x16x64_i8 v[86:89], v[136:139], v[168:171], v[86:89]
	v_mfma_i32_16x16x64_i8 v[30:33], v[144:147], v[168:171], v[30:33]
	v_mfma_i32_16x16x64_i8 v[78:81], v[136:139], v[176:179], v[78:81]
	v_mfma_i32_16x16x64_i8 v[22:25], v[144:147], v[176:179], v[22:25]
	v_mfma_i32_16x16x64_i8 v[70:73], v[136:139], v[190:193], v[70:73]
	v_mfma_i32_16x16x64_i8 v[14:17], v[144:147], v[190:193], v[14:17]
	v_mfma_i32_16x16x64_i8 v[62:65], v[136:139], v[200:203], v[62:65]
	v_mfma_i32_16x16x64_i8 v[2:5], v[144:147], v[200:203], v[2:5]
	v_mfma_i32_16x16x64_i8 v[66:69], v[148:151], v[164:167], v[66:69]
	v_mfma_i32_16x16x64_i8 v[26:29], v[156:159], v[164:167], v[26:29]
	v_mfma_i32_16x16x64_i8 v[58:61], v[148:151], v[172:175], v[58:61]
	v_mfma_i32_16x16x64_i8 v[18:21], v[156:159], v[172:175], v[18:21]
	v_mfma_i32_16x16x64_i8 v[54:57], v[148:151], v[180:183], v[54:57]
	v_mfma_i32_16x16x64_i8 v[10:13], v[156:159], v[180:183], v[10:13]
	v_mfma_i32_16x16x64_i8 v[50:53], v[148:151], v[196:199], v[50:53]
	v_mfma_i32_16x16x64_i8 v[6:9], v[156:159], v[196:199], v[6:9]
	v_mfma_i32_16x16x64_i8 v[66:69], v[152:155], v[168:171], v[66:69]
	v_mfma_i32_16x16x64_i8 v[26:29], v[160:163], v[168:171], v[26:29]
	v_mfma_i32_16x16x64_i8 v[58:61], v[152:155], v[176:179], v[58:61]
	v_mfma_i32_16x16x64_i8 v[18:21], v[160:163], v[176:179], v[18:21]
	v_mfma_i32_16x16x64_i8 v[54:57], v[152:155], v[190:193], v[54:57]
	v_mfma_i32_16x16x64_i8 v[10:13], v[160:163], v[190:193], v[10:13]
	v_mfma_i32_16x16x64_i8 v[50:53], v[152:155], v[200:203], v[50:53]
	v_mfma_i32_16x16x64_i8 v[6:9], v[160:163], v[200:203], v[6:9]
	s_barrier
	s_setprio 0
	v_add_u32_e32 v0, s90, v212
	ds_read_b128 v[132:135], v0
	ds_read_b128 v[136:139], v0 offset:1024
	ds_read_b128 v[140:143], v0 offset:2048
	ds_read_b128 v[144:147], v0 offset:3072
	v_add_u32_e32 v0, s95, v212
	ds_read_b128 v[148:151], v0
	ds_read_b128 v[152:155], v0 offset:1024
	ds_read_b128 v[156:159], v0 offset:2048
	ds_read_b128 v[160:163], v0 offset:3072
	s_mov_b32 m0, s87
	v_lshl_add_u64 v[206:207], v[204:205], 0, s[72:73]
	ds_read_b128 v[164:167], v213 offset:32768
	ds_read_b128 v[168:171], v213 offset:33792
	ds_read_b128 v[172:175], v213 offset:34816
	ds_read_b128 v[176:179], v213 offset:35840
	ds_read_b128 v[180:183], v213 offset:36864
	ds_read_b128 v[190:193], v213 offset:37888
	ds_read_b128 v[196:199], v213 offset:38912
	ds_read_b128 v[200:203], v213 offset:39936
	global_load_lds_dwordx4 v[206:207], off
	v_lshl_add_u64 v[206:207], v[204:205], 0, s[74:75]
	s_mov_b32 m0, s88
	s_nop 0
	global_load_lds_dwordx4 v[206:207], off
	s_waitcnt vmcnt(8)
	s_waitcnt lgkmcnt(0)
	s_setprio 1
	s_barrier
	v_mfma_i32_16x16x64_i8 v[126:129], v[132:135], v[164:167], v[126:129]
	v_mfma_i32_16x16x64_i8 v[102:105], v[140:143], v[164:167], v[102:105]
	v_mfma_i32_16x16x64_i8 v[122:125], v[132:135], v[172:175], v[122:125]
	v_mfma_i32_16x16x64_i8 v[94:97], v[140:143], v[172:175], v[94:97]
	v_mfma_i32_16x16x64_i8 v[118:121], v[132:135], v[180:183], v[118:121]
	v_mfma_i32_16x16x64_i8 v[46:49], v[140:143], v[180:183], v[46:49]
	v_mfma_i32_16x16x64_i8 v[110:113], v[132:135], v[196:199], v[110:113]
	v_mfma_i32_16x16x64_i8 v[38:41], v[140:143], v[196:199], v[38:41]
	v_mfma_i32_16x16x64_i8 v[126:129], v[136:139], v[168:171], v[126:129]
	v_mfma_i32_16x16x64_i8 v[102:105], v[144:147], v[168:171], v[102:105]
	v_mfma_i32_16x16x64_i8 v[122:125], v[136:139], v[176:179], v[122:125]
	v_mfma_i32_16x16x64_i8 v[94:97], v[144:147], v[176:179], v[94:97]
	v_mfma_i32_16x16x64_i8 v[118:121], v[136:139], v[190:193], v[118:121]
	v_mfma_i32_16x16x64_i8 v[46:49], v[144:147], v[190:193], v[46:49]
	v_mfma_i32_16x16x64_i8 v[110:113], v[136:139], v[200:203], v[110:113]
	v_mfma_i32_16x16x64_i8 v[38:41], v[144:147], v[200:203], v[38:41]
	v_mfma_i32_16x16x64_i8 v[114:117], v[148:151], v[164:167], v[114:117]
	v_mfma_i32_16x16x64_i8 v[82:85], v[156:159], v[164:167], v[82:85]
	v_mfma_i32_16x16x64_i8 v[106:109], v[148:151], v[172:175], v[106:109]
	v_mfma_i32_16x16x64_i8 v[74:77], v[156:159], v[172:175], v[74:77]
	v_mfma_i32_16x16x64_i8 v[98:101], v[148:151], v[180:183], v[98:101]
	v_mfma_i32_16x16x64_i8 v[42:45], v[156:159], v[180:183], v[42:45]
	v_mfma_i32_16x16x64_i8 v[90:93], v[148:151], v[196:199], v[90:93]
	v_mfma_i32_16x16x64_i8 v[34:37], v[156:159], v[196:199], v[34:37]
	v_mfma_i32_16x16x64_i8 v[114:117], v[152:155], v[168:171], v[114:117]
	v_mfma_i32_16x16x64_i8 v[82:85], v[160:163], v[168:171], v[82:85]
	v_mfma_i32_16x16x64_i8 v[106:109], v[152:155], v[176:179], v[106:109]
	v_mfma_i32_16x16x64_i8 v[74:77], v[160:163], v[176:179], v[74:77]
	v_mfma_i32_16x16x64_i8 v[98:101], v[152:155], v[190:193], v[98:101]
	v_mfma_i32_16x16x64_i8 v[42:45], v[160:163], v[190:193], v[42:45]
	v_mfma_i32_16x16x64_i8 v[90:93], v[152:155], v[200:203], v[90:93]
	v_mfma_i32_16x16x64_i8 v[34:37], v[160:163], v[200:203], v[34:37]
	s_barrier
; #define PG8_STAGE(bufoff, gbase, unused) do { _Pragma("unroll") for (int _i = 0; _i < 2; ++_i) \
;         __builtin_amdgcn_global_load_lds((const unsigned*)((const char*)(gbase) + voff + _i * 8192), (LAS unsigned*)(lds + (bufoff) + ldsw + _i * 8192), 16, 0, 0); } while (0)
; #define PG8_LDA(dst, b, h) do { _Pragma("unroll") for (int m = 0; m < 4; ++m) _Pragma("unroll") for (int k = 0; k < 2; ++k) dst[m][k] = *(const LAS bf16x8*)(lds + PG8_SA(b, h) + aoff + m * 2048 + (FP8 ? k * 16 : k * 1024)); } while (0)
; #define PG8_WAIT_V(n) asm volatile("s_waitcnt vmcnt(" #n ")" ::: "memory")
; #define PG8_WAIT_L(n) asm volatile("s_waitcnt lgkmcnt(" #n ")" ::: "memory")
; #define PG8_BAR __builtin_amdgcn_s_barrier()
; #define PG8_SCHED __builtin_amdgcn_sched_barrier(0)
; template <class Epi, class Sched, bool ALIGN_EPI, bool SP2, int MODE  >
; __device__ __forceinline__ void gemm_phase(LAS unsigned char* lds, const Gemm g, const Sched S, const Epi E, unsigned long long& probe_acc, int epi_id, int wv) {
;     ...
;             PG8_LDA(At, 1, 1); PG8_STAGE(PG8_SB(1, 0), b3, voffB); PG8_STAGE(PG8_SB(1, 1), b3 + hB, voffB); PG8_STAGE(PG8_SA(1, 0), a3, voffA);
;             PG8_WAIT_V(8); PG8_WAIT_L(0); PG8_BAR; PG8_MMA(1, 0, At, B0); PG8_MMA(1, 1, At, B1); PG8_BAR; PG8_SCHED;
;     ...
;         if constexpr (ALIGN_EPI) { if (wr == 0) PG8_BAR; }
	s_setprio 0
	s_mov_b32 m0, s91
	v_lshl_add_u64 v[206:207], v[184:185], 0, s[76:77]
	ds_read_b128 v[164:167], v213 offset:49152
	ds_read_b128 v[168:171], v213 offset:50176
	ds_read_b128 v[172:175], v213 offset:51200
	ds_read_b128 v[176:179], v213 offset:52224
	ds_read_b128 v[180:183], v213 offset:53248
	ds_read_b128 v[190:193], v213 offset:54272
	ds_read_b128 v[196:199], v213 offset:55296
	ds_read_b128 v[200:203], v213 offset:56320
	global_load_lds_dwordx4 v[206:207], off
	v_lshl_add_u64 v[206:207], v[184:185], 0, s[78:79]
	s_mov_b32 m0, s92
	s_nop 0
	global_load_lds_dwordx4 v[206:207], off
	v_lshl_add_u64 v[206:207], v[184:185], 0, s[80:81]
	s_mov_b32 m0, s2
	v_lshl_add_u64 v[184:185], v[184:185], 0, s[82:83]
	global_load_lds_dwordx4 v[206:207], off
	s_mov_b32 m0, s3
	s_nop 0
	global_load_lds_dwordx4 v[184:185], off
	v_lshl_add_u64 v[184:185], v[204:205], 0, s[76:77]
	s_mov_b32 m0, s93
	s_nop 0
	global_load_lds_dwordx4 v[184:185], off
	v_lshl_add_u64 v[184:185], v[204:205], 0, s[78:79]
	s_mov_b32 m0, s94
	s_nop 0
	global_load_lds_dwordx4 v[184:185], off
	s_waitcnt vmcnt(8)
	s_waitcnt lgkmcnt(0)
	s_setprio 1
	s_barrier
	v_mfma_i32_16x16x64_i8 v[86:89], v[132:135], v[164:167], v[86:89]
	v_mfma_i32_16x16x64_i8 v[30:33], v[140:143], v[164:167], v[30:33]
	v_mfma_i32_16x16x64_i8 v[78:81], v[132:135], v[172:175], v[78:81]
	v_mfma_i32_16x16x64_i8 v[22:25], v[140:143], v[172:175], v[22:25]
	v_mfma_i32_16x16x64_i8 v[70:73], v[132:135], v[180:183], v[70:73]
	v_mfma_i32_16x16x64_i8 v[14:17], v[140:143], v[180:183], v[14:17]
	v_mfma_i32_16x16x64_i8 v[62:65], v[132:135], v[196:199], v[62:65]
	v_mfma_i32_16x16x64_i8 v[2:5], v[140:143], v[196:199], v[2:5]
	v_mfma_i32_16x16x64_i8 v[86:89], v[136:139], v[168:171], v[86:89]
	v_mfma_i32_16x16x64_i8 v[30:33], v[144:147], v[168:171], v[30:33]
	v_mfma_i32_16x16x64_i8 v[78:81], v[136:139], v[176:179], v[78:81]
	v_mfma_i32_16x16x64_i8 v[22:25], v[144:147], v[176:179], v[22:25]
	v_mfma_i32_16x16x64_i8 v[70:73], v[136:139], v[190:193], v[70:73]
	v_mfma_i32_16x16x64_i8 v[14:17], v[144:147], v[190:193], v[14:17]
	v_mfma_i32_16x16x64_i8 v[62:65], v[136:139], v[200:203], v[62:65]
	v_mfma_i32_16x16x64_i8 v[2:5], v[144:147], v[200:203], v[2:5]
	v_mfma_i32_16x16x64_i8 v[66:69], v[148:151], v[164:167], v[66:69]
	v_mfma_i32_16x16x64_i8 v[26:29], v[156:159], v[164:167], v[26:29]
	v_mfma_i32_16x16x64_i8 v[58:61], v[148:151], v[172:175], v[58:61]
	v_mfma_i32_16x16x64_i8 v[18:21], v[156:159], v[172:175], v[18:21]
	v_mfma_i32_16x16x64_i8 v[54:57], v[148:151], v[180:183], v[54:57]
	v_mfma_i32_16x16x64_i8 v[10:13], v[156:159], v[180:183], v[10:13]
	v_mfma_i32_16x16x64_i8 v[50:53], v[148:151], v[196:199], v[50:53]
	v_mfma_i32_16x16x64_i8 v[6:9], v[156:159], v[196:199], v[6:9]
	v_mfma_i32_16x16x64_i8 v[66:69], v[152:155], v[168:171], v[66:69]
	v_mfma_i32_16x16x64_i8 v[26:29], v[160:163], v[168:171], v[26:29]
	v_mfma_i32_16x16x64_i8 v[58:61], v[152:155], v[176:179], v[58:61]
	v_mfma_i32_16x16x64_i8 v[18:21], v[160:163], v[176:179], v[18:21]
	v_mfma_i32_16x16x64_i8 v[54:57], v[152:155], v[190:193], v[54:57]
	v_mfma_i32_16x16x64_i8 v[10:13], v[160:163], v[190:193], v[10:13]
	v_mfma_i32_16x16x64_i8 v[50:53], v[152:155], v[200:203], v[50:53]
	v_mfma_i32_16x16x64_i8 v[6:9], v[160:163], v[200:203], v[6:9]
	s_barrier
	s_setprio 0
	s_add_i32 s14, s14, 2
	s_add_u32 s16, s16, 0x8000
	s_addc_u32 s17, s17, 0
	s_cmp_gt_u32 s14, 13
	s_mov_b64 s[28:29], s[30:31]
	s_cbranch_scc0 .LBB0_326
	v_readlane_b32 s14, v255, 15
	v_readlane_b32 s15, v255, 16
	s_andn2_b64 vcc, s[24:25], s[14:15]
	s_and_b64 vcc, vcc, exec
	s_cbranch_vccnz .LBB0_329
	v_readlane_b32 s14, v255, 11
	v_readlane_b32 s15, v255, 12
	s_and_b64 vcc, exec, s[14:15]
	s_cbranch_vccz .LBB0_329
	s_barrier
